# attention: LDS-DMA saddr addressing; last QK MFMA writes scores directly (no per-tile 8x v_mov_b64 copy); on top of -mrun fold and upproj zero skip
# speedup vs baseline: 1.0283x; 1.0113x over previous
; __device__ __forceinline__ void attn_unit(LAS unsigned char* lds, const bf16_t* Qg, const bf16_t* Kg, const bf16_t* Vtg, bf16_t* Og, int bh, int qb, int tid_, int wave, int lane_) {
;     int tid = tid_; asm volatile("" : "+v"(tid));
;     const int lane = tid & 63;
;     const int rg = wave & 3, kh = wave >> 2, r = lane & 31, hi = lane >> 5;
;     const int b = bh >> 2, h = bh & 3;
;     const int nt = 2 * (qb + 1);
;     const float NEG = -1e30f;
;     bf16x8 qf[12];
;     { const bf16_t* qp = Qg + ((size_t)bh * SEQ + 128 * qb + 32 * rg + r) * QKD + 8 * hi;
; #pragma unroll
;       for (int kk = 0; kk < 12; ++kk) qf[kk] = *(const bf16x8*)(qp + 16 * kk); }
;     const unsigned char* kg = (const unsigned char*)(Kg + (size_t)bh * SEQ * QKD);
;     const unsigned char* vg = (const unsigned char*)(Vtg + (size_t)bh * VD * SEQ);
;     unsigned kgo[3], vgo[2];
; #pragma unroll
;     for (int i = 0; i < 3; ++i) { const int a = (wave * 3 + i) * 1024 + lane * 16, row = a / 384, cp = (a % 384) >> 4, cl = (cp & ~7) | ((cp ^ (row >> 1)) & 7); kgo[i] = (unsigned)(row * 384 + cl * 16); }
; #pragma unroll
;     for (int i = 0; i < 2; ++i) { const int a = (wave * 2 + i) * 1024 + lane * 16, row = a >> 7, cp = (a & 127) >> 4, cl = (cp ^ (row >> 1)) & 7; vgo[i] = (unsigned)(row * (SEQ * 2) + cl * 16); }
;     const int sw = (r >> 1) & 7;
;     unsigned kro[4], vro[2];
; #pragma unroll
;     for (int q = 0; q < 4; ++q) kro[q] = (unsigned)((32 * kh + r) * 384 + (((2 * q + hi) ^ sw) * 16));
; #pragma unroll
;     for (int s = 0; s < 2; ++s) vro[s] = (unsigned)(VRING + r * 128 + (((4 * kh + 2 * s + hi) ^ sw) * 16));
;     f32x16 o[4]; float mrun = NEG, lrun = 0.f;
; #pragma unroll
;     for (int dt = 0; dt < 4; ++dt)
; #pragma unroll
;         for (int i = 0; i < 16; ++i) o[dt][i] = 0.f;
;     ATT_ISSUE_K(0, 0); ATT_ISSUE_V(0, 0); ATT_ISSUE_K(1, 1);
;     ATT_ISSUE_K((2 < nt) ? 2 : nt - 1, 2); ATT_ISSUE_V(1, 1);
;     asm volatile("s_waitcnt vmcnt(5)" ::: "memory"); __builtin_amdgcn_s_barrier(); asm volatile("" ::: "memory");
;     f32x16 sc, sn;
;     {
; #pragma unroll
;       for (int i = 0; i < 16; ++i) sc[i] = 0.f;
; #pragma unroll
;       for (int kk = 0; kk < 12; ++kk) { const bf16x8 kf = *(const LAS bf16x8*)(lds + KRING + kro[kk & 3] + (kk >> 2) * 128); sc = MFMA32(kf, qf[kk], sc); if ((kk & 3) == 3) __builtin_amdgcn_sched_barrier(0); } }
.LBB0_475:
	s_ashr_i32 s40, s72, 3
	s_sub_i32 s0, 63, s40
	s_and_b32 s73, s72, 7
	s_lshl_b32 s66, s0, 7
	s_mov_b64 s[8:9], s[88:89]
	s_lshl_b32 s44, s0, 1
	s_lshl_b32 s41, s73, 13
	s_ashr_i32 s88, s66, 31
	v_mov_b32_e32 v4, v254
	s_add_u32 s0, s41, s66
	s_addc_u32 s4, 0, s88
	v_and_b32_e32 v180, 31, v4
	s_or_b32 s0, s0, s97
	v_or_b32_e32 v0, s0, v180
	v_bfe_u32 v24, v4, 5, 1
	v_mad_u64_u32 v[0:1], s[0:1], v0, s61, v[178:179]
	v_mad_i32_i24 v1, s4, v195, v1
	v_lshlrev_b32_e32 v176, 4, v24
	v_and_b32_e32 v181, 63, v4
	v_lshl_add_u64 v[0:1], v[0:1], 0, v[176:177]
	global_load_dwordx4 v[96:99], v[0:1], off
	global_load_dwordx4 v[100:103], v[0:1], off offset:32
	global_load_dwordx4 v[104:107], v[0:1], off offset:64
	global_load_dwordx4 v[108:111], v[0:1], off offset:96
	global_load_dwordx4 v[112:115], v[0:1], off offset:128
	global_load_dwordx4 v[116:119], v[0:1], off offset:160
	global_load_dwordx4 v[120:123], v[0:1], off offset:192
	global_load_dwordx4 v[124:127], v[0:1], off offset:224
	global_load_dwordx4 v[128:131], v[0:1], off offset:256
	global_load_dwordx4 v[132:135], v[0:1], off offset:288
	global_load_dwordx4 v[136:139], v[0:1], off offset:320
	global_load_dwordx4 v[140:143], v[0:1], off offset:352
	v_lshlrev_b32_e32 v0, 4, v181
	v_or_b32_e32 v1, s59, v0
	v_mul_hi_i32 v2, v1, s42
	v_lshrrev_b32_e32 v3, 31, v2
	v_ashrrev_i32_e32 v2, 6, v2
	v_add_u32_e32 v2, v2, v3
	v_mul_i32_i24_e32 v3, 0x180, v2
	v_lshlrev_b32_e32 v2, 3, v2
	v_sub_u32_e32 v1, v1, v3
	v_and_b32_e32 v2, 0x70, v2
	v_xad_u32 v176, v2, v1, v3
	v_or_b32_e32 v1, s60, v0
	v_mul_hi_i32 v2, v1, s42
	v_lshrrev_b32_e32 v3, 31, v2
	v_ashrrev_i32_e32 v2, 6, v2
	v_add_u32_e32 v2, v2, v3
	v_mul_i32_i24_e32 v3, 0x180, v2
	v_lshlrev_b32_e32 v2, 3, v2
	v_sub_u32_e32 v1, v1, v3
	v_and_b32_e32 v2, 0x70, v2
	v_xad_u32 v182, v2, v1, v3
	v_or_b32_e32 v1, s67, v0
	v_mul_hi_i32 v2, v1, s42
	v_lshrrev_b32_e32 v3, 31, v2
	v_ashrrev_i32_e32 v2, 6, v2
	v_add_u32_e32 v2, v2, v3
	v_mul_i32_i24_e32 v3, 0x180, v2
	v_lshlrev_b32_e32 v2, 3, v2
	s_mul_i32 s0, s73, 0x300000
	s_lshl_b32 s1, s73, 21
	v_sub_u32_e32 v1, v1, v3
	v_and_b32_e32 v2, 0x70, v2
	v_readlane_b32 s4, v255, 32
	v_xad_u32 v184, v2, v1, v3
	v_readlane_b32 s5, v255, 33
	s_add_u32 s92, s4, s0
	v_or_b32_e32 v0, s68, v0
	v_lshlrev_b32_e32 v2, 4, v4
	v_and_b32_e32 v3, 48, v4
	s_mov_b32 m0, s71
	s_addc_u32 s93, s5, 0
	v_lshlrev_b32_e32 v1, 7, v0
	v_bitop3_b32 v2, v2, v3, s86 bitop3:0x6c
	v_or_b32_e32 v0, 0x400, v0
	v_and_or_b32 v186, v1, s62, v2
	v_lshrrev_b32_e32 v1, 8, v0
	s_add_i32 s89, s44, 2
	global_load_lds_dwordx4 v176, s[92:93]
	s_mov_b32 m0, s91
	v_readlane_b32 s0, v255, 52
	v_xor_b32_e32 v1, v1, v4
	v_lshlrev_b32_e32 v0, 7, v0
	global_load_lds_dwordx4 v182, s[92:93]
	s_mov_b32 m0, s74
	s_add_u32 s94, s0, s1
	v_readlane_b32 s0, v255, 53
	v_and_b32_e32 v0, 0xffffc000, v0
	v_lshlrev_b32_e32 v1, 4, v1
	global_load_lds_dwordx4 v184, s[92:93]
	s_addc_u32 s95, s0, 0
	s_mov_b32 m0, s96
	v_and_or_b32 v188, v1, s86, v0
	global_load_lds_dwordx4 v186, s[94:95]
	s_mov_b32 m0, s43
	s_add_u32 s38, s92, 0x6000
	global_load_lds_dwordx4 v188, s[94:95]
	s_addc_u32 s39, s93, 0
	s_mov_b32 m0, s75
	s_or_b32 s45, s44, 1
	global_load_lds_dwordx4 v176, s[38:39]
	s_mov_b32 m0, s90
	s_add_u32 s0, s92, 0xc000
	global_load_lds_dwordx4 v182, s[38:39]
	s_mov_b32 m0, s2
	s_addc_u32 s1, s93, 0
	global_load_lds_dwordx4 v184, s[38:39]
	s_mov_b32 m0, s85
	v_mov_b32_e32 v187, v177
	global_load_lds_dwordx4 v176, s[0:1]
	s_mov_b32 m0, s87
	v_lshl_add_u64 v[0:1], s[94:95], 0, v[186:187]
	v_mov_b32_e32 v189, v177
	global_load_lds_dwordx4 v182, s[0:1]
	s_mov_b32 m0, s3
	v_lshl_add_u64 v[2:3], s[94:95], 0, v[188:189]
	global_load_lds_dwordx4 v184, s[0:1]
	v_lshl_add_u64 v[0:1], v[0:1], 0, s[78:79]
	s_mov_b32 m0, s33
	v_or_b32_e32 v5, s70, v24
	global_load_lds_dwordx4 v[0:1], off
	v_lshl_add_u64 v[0:1], v[2:3], 0, s[78:79]
	s_mov_b32 m0, s10
	s_mov_b32 s48, s49
	global_load_lds_dwordx4 v[0:1], off
	v_lshrrev_b32_e32 v0, 1, v4
	v_or_b32_e32 v1, s69, v180
	v_bfe_u32 v4, v4, 1, 3
	v_mul_lo_u32 v1, v1, s61
	v_bitop3_b32 v0, v24, v0, 7 bitop3:0x78
	v_lshl_or_b32 v191, v0, 4, v1
	v_bitop3_b32 v0, v24, v4, 2 bitop3:0x36
	v_lshl_or_b32 v197, v0, 4, v1
	v_bitop3_b32 v0, v24, v4, 4 bitop3:0x36
	v_lshl_or_b32 v199, v0, 4, v1
	v_bitop3_b32 v0, v24, v4, 6 bitop3:0x36
	s_waitcnt vmcnt(5)
	s_barrier
	v_add_u32_e32 v25, 0, v191
	v_lshl_or_b32 v200, v0, 4, v1
	ds_read_b128 v[0:3], v25
	v_bitop3_b32 v6, v24, v4, s70 bitop3:0x36
	v_bitop3_b32 v4, v5, v4, 2 bitop3:0x36
	v_add_u32_e32 v26, 0, v197
	v_lshlrev_b32_e32 v201, 4, v6
	v_lshlrev_b32_e32 v202, 4, v4
	ds_read_b128 v[4:7], v26
	s_waitcnt vmcnt(0) lgkmcnt(0)
	v_mfma_f32_32x32x16_bf16 v[64:79], v[0:3], v[96:99], 0
	v_add_u32_e32 v27, 0, v199
	ds_read_b128 v[0:3], v27
	v_add_u32_e32 v28, 0, v200
	ds_read_b128 v[16:19], v28
	s_mov_b32 s50, s49
	s_mov_b32 s51, s49
	s_mov_b32 s52, s49
	v_mfma_f32_32x32x16_bf16 v[64:79], v[4:7], v[100:103], v[64:79]
	s_mov_b32 s53, s49
	s_mov_b32 s54, s49
	s_mov_b32 s55, s49
	s_mov_b32 s56, s49
	s_mov_b32 s57, s49
	s_mov_b32 s58, s49
	s_mov_b32 s0, s59
	s_waitcnt lgkmcnt(1)
	v_mfma_f32_32x32x16_bf16 v[64:79], v[0:3], v[104:107], v[64:79]
	s_mov_b32 s59, s49
	s_mov_b32 s1, s60
	s_mov_b32 s60, s49
	s_mov_b32 s61, s49
	s_mov_b32 s62, s49
	s_mov_b32 s63, s49
	v_mov_b64_e32 v[0:1], s[48:49]
	s_waitcnt lgkmcnt(0)
	v_mfma_f32_32x32x16_bf16 v[64:79], v[16:19], v[108:111], v[64:79]
	s_mov_b32 s84, 1
	v_mov_b32_e32 v183, v177
	v_mov_b32_e32 v185, v177
	v_mov_b64_e32 v[2:3], s[50:51]
	v_mov_b64_e32 v[4:5], s[52:53]
	v_mov_b64_e32 v[6:7], s[54:55]
	v_mov_b64_e32 v[8:9], s[56:57]
	v_mov_b64_e32 v[10:11], s[58:59]
	v_mov_b64_e32 v[12:13], s[60:61]
	v_mov_b64_e32 v[14:15], s[62:63]
	s_mov_b32 s62, 0xfffdc000
	s_movk_i32 s61, 0x180
	s_mov_b32 s60, s1
	s_mov_b32 s59, s0
	ds_read_b128 v[16:19], v25 offset:128
	ds_read_b128 v[20:23], v26 offset:128
	s_waitcnt lgkmcnt(1)
	v_mfma_f32_32x32x16_bf16 v[64:79], v[16:19], v[112:115], v[64:79]
	s_waitcnt lgkmcnt(0)
	v_mfma_f32_32x32x16_bf16 v[64:79], v[20:23], v[116:119], v[64:79]
	ds_read_b128 v[16:19], v27 offset:128
	ds_read_b128 v[20:23], v28 offset:128
	s_waitcnt lgkmcnt(1)
	v_mfma_f32_32x32x16_bf16 v[64:79], v[16:19], v[120:123], v[64:79]
	s_waitcnt lgkmcnt(0)
	v_mfma_f32_32x32x16_bf16 v[64:79], v[20:23], v[124:127], v[64:79]
	ds_read_b128 v[16:19], v25 offset:256
	ds_read_b128 v[20:23], v26 offset:256
	s_waitcnt lgkmcnt(1)
	v_mfma_f32_32x32x16_bf16 v[64:79], v[16:19], v[128:131], v[64:79]
	s_waitcnt lgkmcnt(0)
	v_mfma_f32_32x32x16_bf16 v[64:79], v[20:23], v[132:135], v[64:79]
	ds_read_b128 v[16:19], v27 offset:256
	ds_read_b128 v[20:23], v28 offset:256
	s_waitcnt lgkmcnt(1)
	v_mfma_f32_32x32x16_bf16 v[64:79], v[16:19], v[136:139], v[64:79]
	s_waitcnt lgkmcnt(0)
	v_mfma_f32_32x32x16_bf16 v[80:95], v[20:23], v[140:143], v[64:79]
	s_waitcnt lgkmcnt(0)
	s_barrier
; #define LAS __attribute__((address_space(3)))
; __device__ __forceinline__ float max_xor32(float x) { const u32x2 r = __builtin_amdgcn_permlane32_swap(__float_as_uint(x), __float_as_uint(x), false, false); return fmaxf(__uint_as_float(r.x), __uint_as_float(r.y)); }
; #define MFMA32(a, b, c) __builtin_amdgcn_mfma_f32_32x32x16_bf16((a), (b), (c), 0, 0, 0)
; #define ATT_KRD(dst, g) do { _Pragma("unroll") for (int q_ = 0; q_ < 4; ++q_) dst[q_] = *(const LAS bf16x8*)(kb + kro[q_] + (g) * 128); } while (0)
; __device__ __forceinline__ void attn_unit(LAS unsigned char* lds, const bf16_t* Qg, const bf16_t* Kg, const bf16_t* Vtg, bf16_t* Og, int bh, int qb, int tid_, int wave, int lane_) {
;     ...
;     const float NINF = -__builtin_inff();
;     int s0 = 0, s1 = 1, s2 = 2;
;     for (int j = 0; j < nt; ++j) {
;         const int relc = 64 * (j - 2 * qb) + 32 * kh - 32 * rg;
;         const int j3 = (j + 3 < nt) ? j + 3 : nt - 1, j2 = (j + 2 < nt) ? j + 2 : nt - 1;
;         const LAS unsigned char* kb = lds + KRING + s1 * KTILE;
;         const LAS unsigned char* vb = lds + s0 * VTILE;
;         if (relc >= 0) {
;             const int thr = (relc == 0) ? r : -1;
; #pragma unroll
;             for (int i = 0; i < 16; ++i) { const int key = (i & 3) + 8 * (i >> 2) + 4 * hi; if (key > thr) sc[i] = NINF; }
;         }
;     ...
;         bf16x8 fa[4], fb[4];
;         ATT_KRD(fa, 0); ATT_KRD(fb, 1);
; #pragma unroll
;         for (int i = 0; i < 16; ++i) sn[i] = 0.f;
;         float mx = sc[0];
; #pragma unroll
;         for (int i = 1; i < 16; ++i) mx = fmaxf(mx, sc[i]);
;         mx = max_xor32(mx);
; #pragma unroll
;         for (int q = 0; q < 4; ++q) sn = MFMA32(fa[q], qf[q], sn);
;         ATT_KRD(fa, 2);
;         __builtin_amdgcn_sched_barrier(0);
;         if (__builtin_amdgcn_ballot_w64(mx > mrun + 8.f) != 0ull) {
;             const float mnew = fmaxf(mrun, mx); const float alpha = __builtin_amdgcn_exp2f(mrun - mnew); mrun = mnew; lrun *= alpha;
; #pragma unroll
;             for (int dt = 0; dt < 4; ++dt) o[dt] = o[dt] * alpha;
;         }
	v_lshlrev_b32_e32 v198, 2, v24
	s_lshl_b32 s50, s40, 7
	v_readlane_b32 s0, v255, 54
	v_mov_b64_e32 v[30:31], v[14:15]
	v_mov_b64_e32 v[46:47], v[14:15]
	v_mov_b64_e32 v[62:63], v[14:15]
	v_lshl_add_u32 v203, v180, 7, 0
	s_add_i32 s51, s0, s50
	v_mov_b32_e32 v204, 0xf149f2ca
	v_mov_b32_e32 v226, 0
	v_mov_b32_e32 v227, v226
	v_mov_b32_e32 v228, v226
	v_mov_b32_e32 v229, v226
	v_mov_b32_e32 v230, v226
	v_mov_b32_e32 v231, v226
	v_mov_b32_e32 v232, v226
	v_mov_b32_e32 v233, v226
	v_mov_b32_e32 v234, v226
	v_mov_b32_e32 v235, v226
	v_mov_b32_e32 v236, v226
	v_mov_b32_e32 v237, v226
	v_mov_b32_e32 v238, v226
	v_mov_b32_e32 v239, v226
	v_mov_b32_e32 v240, v226
	v_mov_b32_e32 v241, v226
	v_mov_b32_e32 v242, 0xff7fffff
	v_mov_b32_e32 v243, 0
	v_mov_b64_e32 v[28:29], v[12:13]
	v_mov_b64_e32 v[26:27], v[10:11]
	v_mov_b64_e32 v[24:25], v[8:9]
	v_mov_b64_e32 v[22:23], v[6:7]
	v_mov_b64_e32 v[20:21], v[4:5]
	v_mov_b64_e32 v[18:19], v[2:3]
	v_mov_b64_e32 v[16:17], v[0:1]
	v_mov_b64_e32 v[44:45], v[12:13]
	v_mov_b64_e32 v[42:43], v[10:11]
	v_mov_b64_e32 v[40:41], v[8:9]
	v_mov_b64_e32 v[38:39], v[6:7]
	v_mov_b64_e32 v[36:37], v[4:5]
	v_mov_b64_e32 v[34:35], v[2:3]
	v_mov_b64_e32 v[32:33], v[0:1]
	v_mov_b64_e32 v[60:61], v[12:13]
	v_mov_b64_e32 v[58:59], v[10:11]
	v_mov_b64_e32 v[56:57], v[8:9]
	v_mov_b64_e32 v[54:55], v[6:7]
	v_mov_b64_e32 v[52:53], v[4:5]
	v_mov_b64_e32 v[50:51], v[2:3]
	v_mov_b64_e32 v[48:49], v[0:1]
	v_mov_b32_e32 v190, v177
	s_mov_b32 s0, s49
	s_mov_b32 s53, 2
	s_cmp_lt_i32 s51, 0
	s_mov_b32 s54, s0
	s_cbranch_scc1 .LBB0_477
.LBB0_476:
	s_cmp_eq_u32 s51, 0
	s_cselect_b64 vcc, -1, 0
	v_cndmask_b32_e32 v213, -1, v180, vcc
	v_sub_u32_e32 v213, v213, v198
	v_cmp_gt_i32_e64 s[34:35], 26, v213
	v_cmp_gt_i32_e64 s[36:37], 27, v213
	v_cmp_gt_i32_e64 s[30:31], 25, v213
	s_and_b64 s[34:35], s[36:37], s[34:35]
	v_cmp_gt_i32_e64 s[28:29], 24, v213
	s_and_b64 s[30:31], s[34:35], s[30:31]
	v_cmp_gt_i32_e64 s[26:27], 19, v213
	s_and_b64 s[28:29], s[30:31], s[28:29]
	v_cmp_gt_i32_e64 s[24:25], 18, v213
	s_and_b64 s[26:27], s[28:29], s[26:27]
	v_cmp_gt_i32_e64 s[22:23], 17, v213
	s_and_b64 s[24:25], s[26:27], s[24:25]
	v_cmp_gt_i32_e64 s[20:21], 16, v213
	s_and_b64 s[22:23], s[24:25], s[22:23]
	v_cmp_gt_i32_e64 s[18:19], 11, v213
	s_and_b64 s[20:21], s[22:23], s[20:21]
	v_cmp_gt_i32_e64 s[16:17], 10, v213
	s_and_b64 s[18:19], s[20:21], s[18:19]
	v_cmp_gt_i32_e64 s[14:15], 9, v213
	s_and_b64 s[16:17], s[18:19], s[16:17]
	v_cmp_gt_i32_e64 s[12:13], 8, v213
	s_and_b64 s[14:15], s[16:17], s[14:15]
	v_cmp_gt_i32_e64 s[6:7], 3, v213
	s_and_b64 s[12:13], s[14:15], s[12:13]
	v_cmp_gt_i32_e64 s[4:5], 2, v213
	s_and_b64 s[6:7], s[12:13], s[6:7]
	v_cmp_gt_i32_e64 s[0:1], 1, v213
	s_and_b64 s[4:5], s[6:7], s[4:5]
	v_cmp_gt_i32_e32 vcc, 0, v213
	s_and_b64 s[0:1], s[4:5], s[0:1]
	s_and_b64 vcc, s[0:1], vcc
	v_cndmask_b32_e64 v95, v95, v196, s[36:37]
	v_cndmask_b32_e64 v94, v94, v196, s[34:35]
	v_cndmask_b32_e64 v93, v93, v196, s[30:31]
	v_cndmask_b32_e64 v92, v92, v196, s[28:29]
	v_cndmask_b32_e64 v91, v91, v196, s[26:27]
	v_cndmask_b32_e64 v90, v90, v196, s[24:25]
	v_cndmask_b32_e64 v89, v89, v196, s[22:23]
	v_cndmask_b32_e64 v88, v88, v196, s[20:21]
	v_cndmask_b32_e64 v87, v87, v196, s[18:19]
	v_cndmask_b32_e64 v86, v86, v196, s[16:17]
	v_cndmask_b32_e64 v85, v85, v196, s[14:15]
	v_cndmask_b32_e64 v84, v84, v196, s[12:13]
	v_cndmask_b32_e64 v83, v83, v196, s[6:7]
	v_cndmask_b32_e64 v82, v82, v196, s[4:5]
	v_cndmask_b32_e64 v81, v81, v196, s[0:1]
	v_cndmask_b32_e32 v80, v80, v196, vcc
	s_branch .LBB0_478
.LBB0_477:
.LBB0_478:
	s_mul_i32 s0, s84, 0x6000
	s_add_i32 s0, s0, 0
	v_add_u32_e32 v148, s0, v191
	ds_read_b128 v[64:67], v148
	v_add_u32_e32 v156, s0, v197
	ds_read_b128 v[144:147], v156
	v_add_u32_e32 v160, s0, v199
	v_add_u32_e32 v192, s0, v200
	ds_read_b128 v[206:209], v192
	ds_read_b128 v[164:167], v148 offset:128
	ds_read_b128 v[152:155], v160
	ds_read_b128 v[168:171], v160 offset:128
	s_waitcnt lgkmcnt(0)
	v_mfma_f32_32x32x16_bf16 v[64:79], v[64:67], v[96:99], v[226:241]
	v_max_f32_e32 v149, v80, v81
	v_max3_f32 v157, v149, v82, v83
	ds_read_b128 v[148:151], v148 offset:256
	s_waitcnt lgkmcnt(5)
	v_mfma_f32_32x32x16_bf16 v[64:79], v[144:147], v[100:103], v[64:79]
	v_max3_f32 v144, v157, v84, v85
	v_max3_f32 v144, v144, v86, v87
	v_max3_f32 v144, v144, v88, v89
	v_max3_f32 v144, v144, v90, v91
	v_max3_f32 v144, v144, v92, v93
	v_max3_f32 v193, v144, v94, v95
	v_mov_b32_e32 v194, v193
	s_waitcnt lgkmcnt(2)
	v_mfma_f32_32x32x16_bf16 v[64:79], v[152:155], v[104:107], v[64:79]
	ds_read_b128 v[172:175], v156 offset:128
	ds_read_b128 v[156:159], v156 offset:256
	ds_read_b128 v[152:155], v160 offset:256
	ds_read_b128 v[160:163], v192 offset:128
	ds_read_b128 v[144:147], v192 offset:256
	v_permlane32_swap_b32_e32 v193, v194
	v_max_f32_e32 v205, v193, v194
	v_mfma_f32_32x32x16_bf16 v[64:79], v[206:209], v[108:111], v[64:79]
	v_cmp_gt_f32_e32 vcc, v205, v242
	s_cbranch_vccz .LBB0_480
; __device__ __forceinline__ void attn_unit(LAS unsigned char* lds, const bf16_t* Qg, const bf16_t* Kg, const bf16_t* Vtg, bf16_t* Og, int bh, int qb, int tid_, int wave, int lane_) {
;     ...
;         if (__builtin_amdgcn_ballot_w64(mx > mrun + 8.f) != 0ull) {
;             const float mnew = fmaxf(mrun, mx); const float alpha = __builtin_amdgcn_exp2f(mrun - mnew); mrun = mnew; lrun *= alpha;
; #pragma unroll
;             for (int dt = 0; dt < 4; ++dt) o[dt] = o[dt] * alpha;
;         }
	v_add_f32_e32 v192, v205, v243
	v_max_f32_e32 v193, v204, v204
	v_max_f32_e32 v193, v193, v192
	v_sub_f32_e32 v192, v204, v193
	v_sub_f32_e32 v244, v243, v193
	v_exp_f32_e32 v192, v192
	v_mov_b32_e32 v204, v193
	v_mov_b32_e32 v243, v193
	v_mov_b32_e32 v242, 0x41000000
	v_pk_mul_f32 v[62:63], v[62:63], v[192:193] op_sel_hi:[1,0]
	v_pk_mul_f32 v[60:61], v[60:61], v[192:193] op_sel_hi:[1,0]
	v_pk_mul_f32 v[58:59], v[58:59], v[192:193] op_sel_hi:[1,0]
	v_pk_mul_f32 v[56:57], v[56:57], v[192:193] op_sel_hi:[1,0]
	v_pk_mul_f32 v[54:55], v[54:55], v[192:193] op_sel_hi:[1,0]
	v_pk_mul_f32 v[52:53], v[52:53], v[192:193] op_sel_hi:[1,0]
	v_pk_mul_f32 v[50:51], v[50:51], v[192:193] op_sel_hi:[1,0]
	v_pk_mul_f32 v[48:49], v[48:49], v[192:193] op_sel_hi:[1,0]
	v_pk_mul_f32 v[46:47], v[46:47], v[192:193] op_sel_hi:[1,0]
	v_pk_mul_f32 v[44:45], v[44:45], v[192:193] op_sel_hi:[1,0]
	v_pk_mul_f32 v[42:43], v[42:43], v[192:193] op_sel_hi:[1,0]
	v_pk_mul_f32 v[40:41], v[40:41], v[192:193] op_sel_hi:[1,0]
	v_pk_mul_f32 v[38:39], v[38:39], v[192:193] op_sel_hi:[1,0]
	v_pk_mul_f32 v[36:37], v[36:37], v[192:193] op_sel_hi:[1,0]
	v_pk_mul_f32 v[34:35], v[34:35], v[192:193] op_sel_hi:[1,0]
	v_pk_mul_f32 v[32:33], v[32:33], v[192:193] op_sel_hi:[1,0]
	v_pk_mul_f32 v[30:31], v[30:31], v[192:193] op_sel_hi:[1,0]
	v_pk_mul_f32 v[28:29], v[28:29], v[192:193] op_sel_hi:[1,0]
	v_pk_mul_f32 v[26:27], v[26:27], v[192:193] op_sel_hi:[1,0]
	v_pk_mul_f32 v[24:25], v[24:25], v[192:193] op_sel_hi:[1,0]
	v_pk_mul_f32 v[22:23], v[22:23], v[192:193] op_sel_hi:[1,0]
	v_pk_mul_f32 v[20:21], v[20:21], v[192:193] op_sel_hi:[1,0]
	v_pk_mul_f32 v[18:19], v[18:19], v[192:193] op_sel_hi:[1,0]
	v_pk_mul_f32 v[16:17], v[16:17], v[192:193] op_sel_hi:[1,0]
	v_pk_mul_f32 v[14:15], v[14:15], v[192:193] op_sel_hi:[1,0]
	v_pk_mul_f32 v[12:13], v[12:13], v[192:193] op_sel_hi:[1,0]
	v_pk_mul_f32 v[10:11], v[10:11], v[192:193] op_sel_hi:[1,0]
	v_pk_mul_f32 v[8:9], v[8:9], v[192:193] op_sel_hi:[1,0]
	v_pk_mul_f32 v[6:7], v[6:7], v[192:193] op_sel_hi:[1,0]
	v_pk_mul_f32 v[4:5], v[4:5], v[192:193] op_sel_hi:[1,0]
	v_pk_mul_f32 v[2:3], v[2:3], v[192:193] op_sel_hi:[1,0]
	v_pk_mul_f32 v[0:1], v[0:1], v[192:193] op_sel_hi:[1,0]
	v_mul_f32_e32 v190, v190, v192
	v_add_f32_e32 v80, v80, v244
	v_add_f32_e32 v81, v81, v244
	v_add_f32_e32 v82, v82, v244
	v_add_f32_e32 v83, v83, v244
	v_add_f32_e32 v84, v84, v244
	v_add_f32_e32 v85, v85, v244
	v_add_f32_e32 v86, v86, v244
	v_add_f32_e32 v87, v87, v244
	v_add_f32_e32 v88, v88, v244
	v_add_f32_e32 v89, v89, v244
	v_add_f32_e32 v90, v90, v244
	v_add_f32_e32 v91, v91, v244
	v_add_f32_e32 v92, v92, v244
	v_add_f32_e32 v93, v93, v244
	v_add_f32_e32 v94, v94, v244
	v_add_f32_e32 v95, v95, v244
	v_add_f32_e32 v64, v64, v244
	v_add_f32_e32 v65, v65, v244
	v_add_f32_e32 v66, v66, v244
	v_add_f32_e32 v67, v67, v244
	v_add_f32_e32 v68, v68, v244
	v_add_f32_e32 v69, v69, v244
	v_add_f32_e32 v70, v70, v244
	v_add_f32_e32 v71, v71, v244
	v_add_f32_e32 v72, v72, v244
	v_add_f32_e32 v73, v73, v244
	v_add_f32_e32 v74, v74, v244
	v_add_f32_e32 v75, v75, v244
	v_add_f32_e32 v76, v76, v244
	v_add_f32_e32 v77, v77, v244
	v_add_f32_e32 v78, v78, v244
	v_add_f32_e32 v79, v79, v244
	v_sub_f32_e32 v226, 0, v193
	v_mov_b32_e32 v227, v226
	v_mov_b32_e32 v228, v226
	v_mov_b32_e32 v229, v226
	v_mov_b32_e32 v230, v226
	v_mov_b32_e32 v231, v226
	v_mov_b32_e32 v232, v226
	v_mov_b32_e32 v233, v226
	v_mov_b32_e32 v234, v226
	v_mov_b32_e32 v235, v226
	v_mov_b32_e32 v236, v226
	v_mov_b32_e32 v237, v226
	v_mov_b32_e32 v238, v226
	v_mov_b32_e32 v239, v226
	v_mov_b32_e32 v240, v226
	v_mov_b32_e32 v241, v226
; __device__ __forceinline__ unsigned pk2(float a, float b) { f32x2_t v = {a, b}; bf16x2v_t r = __builtin_convertvector(v, bf16x2v_t); return __builtin_bit_cast(unsigned, r); }
; __device__ __forceinline__ void attn_unit(LAS unsigned char* lds, const bf16_t* Qg, const bf16_t* Kg, const bf16_t* Vtg, bf16_t* Og, int bh, int qb, int tid_, int wave, int lane_) {
;     ...
;         float ps = 0.f; u32x4 p0, p1;
; #pragma unroll
;         for (int q = 0; q < 4; ++q) sn = MFMA32(fb[q], qf[4 + q], sn);
; #pragma unroll
;         for (int i = 0; i < 8; ++i) { sc[i] = __builtin_amdgcn_exp2f(sc[i] - mrun); ps += sc[i]; }
;         p0.x = pk2(sc[0], sc[1]); p0.y = pk2(sc[2], sc[3]); p0.z = pk2(sc[4], sc[5]); p0.w = pk2(sc[6], sc[7]);
;         __builtin_amdgcn_sched_barrier(0);
; #pragma unroll
;         for (int dt = 0; dt < 4; ++dt) fb[dt] = *(const LAS bf16x8*)(vb + vro[0] + dt * 4096);
;         __builtin_amdgcn_sched_barrier(0);
;         ATT_ISSUE_K(j3, s0);
;         __builtin_amdgcn_sched_barrier(0);
; #pragma unroll
;         for (int q = 0; q < 4; ++q) sn = MFMA32(fa[q], qf[8 + q], sn);
; #pragma unroll
;         for (int i = 8; i < 12; ++i) { sc[i] = __builtin_amdgcn_exp2f(sc[i] - mrun); ps += sc[i]; }
;         p1.x = pk2(sc[8], sc[9]); p1.y = pk2(sc[10], sc[11]);
;         __builtin_amdgcn_sched_barrier(0);
;         ATT_ISSUE_V(j2, s2);
;         __builtin_amdgcn_sched_barrier(0);
; #pragma unroll
;         for (int dt = 0; dt < 4; ++dt) fa[dt] = *(const LAS bf16x8*)(vb + vro[1] + dt * 4096);
;         { const bf16x8 pf0 = __builtin_bit_cast(bf16x8, p0);
;           o[0] = MFMA32(fb[0], pf0, o[0]); o[1] = MFMA32(fb[1], pf0, o[1]); o[2] = MFMA32(fb[2], pf0, o[2]); o[3] = MFMA32(fb[3], pf0, o[3]); }
; #pragma unroll
;         for (int i = 12; i < 16; ++i) { sc[i] = __builtin_amdgcn_exp2f(sc[i] - mrun); ps += sc[i]; }
;         p1.z = pk2(sc[12], sc[13]); p1.w = pk2(sc[14], sc[15]);
;         lrun += ps;
;         __builtin_amdgcn_sched_barrier(0);
;         { const bf16x8 pf1 = __builtin_bit_cast(bf16x8, p1);
;           o[0] = MFMA32(fa[0], pf1, o[0]); o[1] = MFMA32(fa[1], pf1, o[1]); o[2] = MFMA32(fa[2], pf1, o[2]); o[3] = MFMA32(fa[3], pf1, o[3]); }
;         asm volatile("s_waitcnt vmcnt(5) lgkmcnt(0)" ::: "memory"); __builtin_amdgcn_s_barrier(); asm volatile("" ::: "memory");
;         sc = sn;
;         { const int t = s0; s0 = s1; s1 = s2; s2 = t; }
;     }
.LBB0_480:
	v_mfma_f32_32x32x16_bf16 v[64:79], v[164:167], v[112:115], v[64:79]
	v_exp_f32_e32 v192, v80
	v_exp_f32_e32 v193, v81
	v_exp_f32_e32 v194, v82
	s_waitcnt lgkmcnt(0)
	v_mfma_f32_32x32x16_bf16 v[64:79], v[172:175], v[116:119], v[64:79]
	v_exp_f32_e32 v205, v83
	v_exp_f32_e32 v206, v84
	v_exp_f32_e32 v207, v85
	v_exp_f32_e32 v208, v86
	v_mfma_f32_32x32x16_bf16 v[64:79], v[168:171], v[120:123], v[64:79]
	s_add_i32 s0, s52, 3
	v_exp_f32_e32 v209, v87
	s_cmp_lt_u32 s0, s89
	s_cselect_b32 s0, s0, s45
	s_add_i32 s1, s52, 2
	s_cmp_lt_u32 s52, s44
	s_cselect_b32 s48, s1, s45
	v_cvt_pk_bf16_f32 v246, v192, v193
	v_cvt_pk_bf16_f32 v247, v194, v205
	v_cvt_pk_bf16_f32 v248, v206, v207
	v_cvt_pk_bf16_f32 v249, v208, v209
	v_lshl_add_u32 v218, s54, 14, v203
	v_add_u32_e32 v210, 0x12000, v218
	v_add_u32_e32 v172, v210, v201
	ds_read_b128 v[214:217], v172
	ds_read_b128 v[164:167], v172 offset:4096
	ds_read_b128 v[168:171], v172 offset:8192
	ds_read_b128 v[172:175], v172 offset:12288
	v_add_f32_e32 v192, v193, v192
	v_add_f32_e32 v192, v194, v192
	v_add_f32_e32 v192, v205, v192
	v_add_f32_e32 v192, v206, v192
	v_add_f32_e32 v192, v207, v192
	v_add_f32_e32 v192, v208, v192
	v_add_f32_e32 v194, v209, v192
	s_mul_hi_u32 s1, s0, 0x6000
	s_mulk_i32 s0, 0x6000
	s_add_u32 s0, s92, s0
	s_mul_i32 s4, s54, 0x6000
	s_addc_u32 s1, s93, s1
	s_add_i32 s4, s71, s4
	s_mov_b32 m0, s4
	s_waitcnt lgkmcnt(5)
	v_mfma_f32_32x32x16_bf16 v[64:79], v[160:163], v[124:127], v[64:79]
	global_load_lds_dwordx4 v176, s[0:1]
	s_add_i32 m0, s4, 0x400
	s_nop 0
	global_load_lds_dwordx4 v182, s[0:1]
	s_add_i32 m0, s4, 0x800
	s_nop 0
	global_load_lds_dwordx4 v184, s[0:1]
	v_mfma_f32_32x32x16_bf16 v[64:79], v[148:151], v[128:131], v[64:79]
	v_exp_f32_e32 v220, v88
	v_exp_f32_e32 v221, v89
	v_exp_f32_e32 v222, v90
	v_mfma_f32_32x32x16_bf16 v[64:79], v[156:159], v[132:135], v[64:79]
	v_exp_f32_e32 v223, v91
	v_add_f32_e32 v148, v220, v194
	v_add_f32_e32 v148, v221, v148
	v_add_f32_e32 v148, v222, v148
	v_add_f32_e32 v156, v223, v148
	v_cvt_pk_bf16_f32 v250, v220, v221
	v_cvt_pk_bf16_f32 v251, v222, v223
	v_mfma_f32_32x32x16_bf16 v[64:79], v[152:155], v[136:139], v[64:79]
	v_exp_f32_e32 v220, v92
	v_exp_f32_e32 v221, v93
	v_exp_f32_e32 v222, v94
	v_exp_f32_e32 v223, v95
	s_waitcnt lgkmcnt(0)
	v_mfma_f32_32x32x16_bf16 v[80:95], v[144:147], v[140:143], v[64:79]
	s_lshl_b64 s[0:1], s[48:49], 7
	s_add_u32 s0, s94, s0
	s_addc_u32 s1, s95, s1
	s_lshl_b32 s4, s53, 14
	s_add_i32 s4, s4, 0
	s_add_i32 s4, s4, s68
	s_add_i32 m0, s4, 0x12000
	s_nop 0
	global_load_lds_dwordx4 v186, s[0:1]
	s_add_i32 m0, s4, 0x12400
	s_nop 0
	global_load_lds_dwordx4 v188, s[0:1]
	v_add_u32_e32 v219, v210, v202
	v_mfma_f32_32x32x16_bf16 v[48:63], v[214:217], v[246:249], v[48:63]
	ds_read_b128 v[214:217], v219
	ds_read_b128 v[144:147], v219 offset:4096
	ds_read_b128 v[148:151], v219 offset:8192
	ds_read_b128 v[152:155], v219 offset:12288
	v_mfma_f32_32x32x16_bf16 v[32:47], v[164:167], v[246:249], v[32:47]
	v_add_f32_e32 v213, v220, v156
	v_add_f32_e32 v213, v221, v213
	v_add_f32_e32 v213, v222, v213
	v_add_f32_e32 v213, v223, v213
	v_add_f32_e32 v190, v190, v213
	v_mfma_f32_32x32x16_bf16 v[16:31], v[168:171], v[246:249], v[16:31]
	v_cvt_pk_bf16_f32 v252, v220, v221
	v_cvt_pk_bf16_f32 v253, v222, v223
	v_mfma_f32_32x32x16_bf16 v[0:15], v[172:175], v[246:249], v[0:15]
	s_waitcnt lgkmcnt(0)
	v_mfma_f32_32x32x16_bf16 v[48:63], v[214:217], v[250:253], v[48:63]
	s_waitcnt vmcnt(5) lgkmcnt(0)
	s_barrier
	s_add_i32 s52, s52, 1
	s_add_i32 s51, s51, 64
	s_cmp_eq_u32 s89, s52
	v_mfma_f32_32x32x16_bf16 v[32:47], v[144:147], v[250:253], v[32:47]
	v_mfma_f32_32x32x16_bf16 v[16:31], v[148:151], v[250:253], v[16:31]
	v_mfma_f32_32x32x16_bf16 v[0:15], v[152:155], v[250:253], v[0:15]
	s_cbranch_scc1 .LBB0_482
	s_mov_b32 s0, s84
	s_mov_b32 s84, s53
	s_mov_b32 s53, s54
	s_cmp_lt_i32 s51, 0
	s_mov_b32 s54, s0
	s_cbranch_scc0 .LBB0_476
	s_branch .LBB0_477

; __device__ __forceinline__ void attn_unit(LAS unsigned char* lds, const bf16_t* Qg, const bf16_t* Kg, const bf16_t* Vtg, bf16_t* Og, int bh, int qb, int tid_, int wave, int lane_) {
;     int tid = tid_; asm volatile("" : "+v"(tid));
;     const int lane = tid & 63;
;     const int rg = wave & 3, kh = wave >> 2, r = lane & 31, hi = lane >> 5;
;     const int b = bh >> 2, h = bh & 3;
;     const int nt = 2 * (qb + 1);
;     const float NEG = -1e30f;
;     bf16x8 qf[12];
;     { const bf16_t* qp = Qg + ((size_t)bh * SEQ + 128 * qb + 32 * rg + r) * QKD + 8 * hi;
; #pragma unroll
;       for (int kk = 0; kk < 12; ++kk) qf[kk] = *(const bf16x8*)(qp + 16 * kk); }
;     const unsigned char* kg = (const unsigned char*)(Kg + (size_t)bh * SEQ * QKD);
;     const unsigned char* vg = (const unsigned char*)(Vtg + (size_t)bh * VD * SEQ);
;     unsigned kgo[3], vgo[2];
; #pragma unroll
;     for (int i = 0; i < 3; ++i) { const int a = (wave * 3 + i) * 1024 + lane * 16, row = a / 384, cp = (a % 384) >> 4, cl = (cp & ~7) | ((cp ^ (row >> 1)) & 7); kgo[i] = (unsigned)(row * 384 + cl * 16); }
; #pragma unroll
;     for (int i = 0; i < 2; ++i) { const int a = (wave * 2 + i) * 1024 + lane * 16, row = a >> 7, cp = (a & 127) >> 4, cl = (cp ^ (row >> 1)) & 7; vgo[i] = (unsigned)(row * (SEQ * 2) + cl * 16); }
;     const int sw = (r >> 1) & 7;
;     unsigned kro[4], vro[2];
; #pragma unroll
;     for (int q = 0; q < 4; ++q) kro[q] = (unsigned)((32 * kh + r) * 384 + (((2 * q + hi) ^ sw) * 16));
; #pragma unroll
;     for (int s = 0; s < 2; ++s) vro[s] = (unsigned)(VRING + r * 128 + (((4 * kh + 2 * s + hi) ^ sw) * 16));
;     f32x16 o[4]; float mrun = NEG, lrun = 0.f;
; #pragma unroll
;     for (int dt = 0; dt < 4; ++dt)
; #pragma unroll
;         for (int i = 0; i < 16; ++i) o[dt][i] = 0.f;
;     ATT_ISSUE_K(0, 0); ATT_ISSUE_V(0, 0); ATT_ISSUE_K(1, 1);
;     ATT_ISSUE_K((2 < nt) ? 2 : nt - 1, 2); ATT_ISSUE_V(1, 1);
;     asm volatile("s_waitcnt vmcnt(5)" ::: "memory"); __builtin_amdgcn_s_barrier(); asm volatile("" ::: "memory");
;     f32x16 sc, sn;
;     {
; #pragma unroll
;       for (int i = 0; i < 16; ++i) sc[i] = 0.f;
; #pragma unroll
;       for (int kk = 0; kk < 12; ++kk) { const bf16x8 kf = *(const LAS bf16x8*)(lds + KRING + kro[kk & 3] + (kk >> 2) * 128); sc = MFMA32(kf, qf[kk], sc); if ((kk & 3) == 3) __builtin_amdgcn_sched_barrier(0); } }
.LBB0_486:
	s_lshl_b32 s52, s40, 1
	s_ashr_i32 s51, s50, 31
	v_mov_b32_e32 v6, v254
	s_add_u32 s0, s41, s50
	s_barrier
	s_addc_u32 s12, 0, s51
	v_and_b32_e32 v191, 31, v6
	s_or_b32 s0, s0, s97
	v_or_b32_e32 v2, s0, v191
	v_readlane_b32 s0, v255, 36
	v_readlane_b32 s1, v255, 37
	v_bfe_u32 v190, v6, 5, 1
	v_lshlrev_b32_e32 v176, 4, v190
	v_mov_b64_e32 v[0:1], s[0:1]
	v_mad_u64_u32 v[0:1], s[0:1], v2, s61, v[0:1]
	v_mad_i32_i24 v1, s12, v195, v1
	v_and_b32_e32 v181, 63, v6
	v_lshl_add_u64 v[0:1], v[0:1], 0, v[176:177]
	global_load_dwordx4 v[96:99], v[0:1], off
	global_load_dwordx4 v[100:103], v[0:1], off offset:32
	global_load_dwordx4 v[104:107], v[0:1], off offset:64
	global_load_dwordx4 v[108:111], v[0:1], off offset:96
	global_load_dwordx4 v[112:115], v[0:1], off offset:128
	global_load_dwordx4 v[116:119], v[0:1], off offset:160
	global_load_dwordx4 v[120:123], v[0:1], off offset:192
	global_load_dwordx4 v[124:127], v[0:1], off offset:224
	global_load_dwordx4 v[128:131], v[0:1], off offset:256
	global_load_dwordx4 v[132:135], v[0:1], off offset:288
	global_load_dwordx4 v[136:139], v[0:1], off offset:320
	global_load_dwordx4 v[140:143], v[0:1], off offset:352
	v_lshlrev_b32_e32 v0, 4, v181
	v_or_b32_e32 v1, s59, v0
	v_mul_hi_i32 v2, v1, s42
	v_lshrrev_b32_e32 v3, 31, v2
	v_ashrrev_i32_e32 v2, 6, v2
	v_add_u32_e32 v2, v2, v3
	v_mul_i32_i24_e32 v3, 0x180, v2
	v_lshlrev_b32_e32 v2, 3, v2
	v_sub_u32_e32 v1, v1, v3
	v_and_b32_e32 v2, 0x70, v2
	v_xad_u32 v182, v2, v1, v3
	v_or_b32_e32 v1, s60, v0
	v_mul_hi_i32 v2, v1, s42
	v_lshrrev_b32_e32 v3, 31, v2
	v_ashrrev_i32_e32 v2, 6, v2
	v_add_u32_e32 v2, v2, v3
	v_mul_i32_i24_e32 v3, 0x180, v2
	v_lshlrev_b32_e32 v2, 3, v2
	v_sub_u32_e32 v1, v1, v3
	v_and_b32_e32 v2, 0x70, v2
	v_xad_u32 v184, v2, v1, v3
	v_or_b32_e32 v1, s67, v0
	v_mul_hi_i32 v2, v1, s42
	v_lshrrev_b32_e32 v3, 31, v2
	v_ashrrev_i32_e32 v2, 6, v2
	v_add_u32_e32 v2, v2, v3
	v_mul_i32_i24_e32 v3, 0x180, v2
	v_lshlrev_b32_e32 v2, 3, v2
	v_sub_u32_e32 v1, v1, v3
	v_and_b32_e32 v2, 0x70, v2
	v_xad_u32 v186, v2, v1, v3
	v_or_b32_e32 v0, s68, v0
	v_lshlrev_b32_e32 v2, 4, v6
	v_and_b32_e32 v3, 48, v6
	s_mov_b32 m0, s71
	v_lshlrev_b32_e32 v1, 7, v0
	v_bitop3_b32 v2, v2, v3, s86 bitop3:0x6c
	v_or_b32_e32 v0, 0x400, v0
	v_and_or_b32 v176, v1, s62, v2
	v_lshrrev_b32_e32 v1, 8, v0
	global_load_lds_dwordx4 v182, s[92:93]
	s_mov_b32 m0, s91
	v_xor_b32_e32 v1, v1, v6
	v_lshlrev_b32_e32 v0, 7, v0
	global_load_lds_dwordx4 v184, s[92:93]
	s_mov_b32 m0, s74
	v_and_b32_e32 v0, 0xffffc000, v0
	v_lshlrev_b32_e32 v1, 4, v1
	global_load_lds_dwordx4 v186, s[92:93]
	s_mov_b32 m0, s96
	s_or_b32 s44, s52, 1
	v_and_or_b32 v188, v1, s86, v0
	global_load_lds_dwordx4 v176, s[94:95]
	s_mov_b32 m0, s43
	s_cmp_lt_i32 s40, 1
	global_load_lds_dwordx4 v188, s[94:95]
	s_mov_b32 m0, s75
	s_cselect_b32 s0, s44, 2
	global_load_lds_dwordx4 v182, s[38:39]
	s_mov_b32 m0, s90
	s_mul_hi_i32 s1, s0, 0x6000
	s_mulk_i32 s0, 0x6000
	global_load_lds_dwordx4 v184, s[38:39]
	s_mov_b32 m0, s2
	s_add_u32 s0, s92, s0
	global_load_lds_dwordx4 v186, s[38:39]
	s_addc_u32 s1, s93, s1
	s_mov_b32 m0, s85
	v_lshl_add_u64 v[0:1], s[94:95], 0, v[176:177]
	global_load_lds_dwordx4 v182, s[0:1]
	s_mov_b32 m0, s87
	v_mov_b32_e32 v189, v177
	global_load_lds_dwordx4 v184, s[0:1]
	s_mov_b32 m0, s3
	v_lshl_add_u64 v[2:3], s[94:95], 0, v[188:189]
	global_load_lds_dwordx4 v186, s[0:1]
	v_lshl_add_u64 v[0:1], v[0:1], 0, s[78:79]
	s_mov_b32 m0, s33
	s_nop 0
	global_load_lds_dwordx4 v[0:1], off
	v_lshl_add_u64 v[0:1], v[2:3], 0, s[78:79]
	s_mov_b32 m0, s10
	s_nop 0
	global_load_lds_dwordx4 v[0:1], off
	v_lshrrev_b32_e32 v0, 1, v6
	v_or_b32_e32 v1, s69, v191
	v_mul_lo_u32 v1, v1, s61
	v_bitop3_b32 v0, v190, v0, 7 bitop3:0x78
	v_lshl_or_b32 v199, v0, 4, v1
	s_waitcnt vmcnt(5)
	s_barrier
	v_add_u32_e32 v10, 0, v199
	ds_read_b128 v[2:5], v10
	v_bfe_u32 v0, v6, 1, 3
	v_bitop3_b32 v6, v190, v0, 2 bitop3:0x36
	v_lshl_or_b32 v200, v6, 4, v1
	v_add_u32_e32 v11, 0, v200
	ds_read_b128 v[6:9], v11
	s_waitcnt vmcnt(0) lgkmcnt(0)
	v_mfma_f32_32x32x16_bf16 v[64:79], v[2:5], v[96:99], 0
	v_bitop3_b32 v2, v190, v0, 4 bitop3:0x36
	v_lshl_or_b32 v201, v2, 4, v1
	v_add_u32_e32 v12, 0, v201
	ds_read_b128 v[2:5], v12
	v_mfma_f32_32x32x16_bf16 v[64:79], v[6:9], v[100:103], v[64:79]
	v_bitop3_b32 v6, v190, v0, 6 bitop3:0x36
	v_lshl_or_b32 v202, v6, 4, v1
	v_add_u32_e32 v1, 0, v202
	ds_read_b128 v[6:9], v1
	s_waitcnt lgkmcnt(1)
	v_mfma_f32_32x32x16_bf16 v[64:79], v[2:5], v[104:107], v[64:79]
	s_waitcnt lgkmcnt(0)
	v_mfma_f32_32x32x16_bf16 v[64:79], v[6:9], v[108:111], v[64:79]
	ds_read_b128 v[2:5], v10 offset:128
	ds_read_b128 v[6:9], v11 offset:128
	s_waitcnt lgkmcnt(1)
	v_mfma_f32_32x32x16_bf16 v[64:79], v[2:5], v[112:115], v[64:79]
	s_waitcnt lgkmcnt(0)
	v_mfma_f32_32x32x16_bf16 v[64:79], v[6:9], v[116:119], v[64:79]
	ds_read_b128 v[2:5], v12 offset:128
	ds_read_b128 v[6:9], v1 offset:128
	s_waitcnt lgkmcnt(1)
	v_mfma_f32_32x32x16_bf16 v[64:79], v[2:5], v[120:123], v[64:79]
	s_waitcnt lgkmcnt(0)
	v_mfma_f32_32x32x16_bf16 v[64:79], v[6:9], v[124:127], v[64:79]
	ds_read_b128 v[2:5], v10 offset:256
	ds_read_b128 v[6:9], v11 offset:256
	s_waitcnt lgkmcnt(1)
	v_mfma_f32_32x32x16_bf16 v[64:79], v[2:5], v[128:131], v[64:79]
	s_waitcnt lgkmcnt(0)
	v_mfma_f32_32x32x16_bf16 v[64:79], v[6:9], v[132:135], v[64:79]
	ds_read_b128 v[2:5], v12 offset:256
	ds_read_b128 v[6:9], v1 offset:256
	s_waitcnt lgkmcnt(1)
	v_mfma_f32_32x32x16_bf16 v[64:79], v[2:5], v[136:139], v[64:79]
	s_waitcnt lgkmcnt(0)
	v_mfma_f32_32x32x16_bf16 v[80:95], v[6:9], v[140:143], v[64:79]
	s_waitcnt lgkmcnt(0)
	s_barrier
	s_cmp_lt_i32 s40, 0
	s_cbranch_scc1 .LBB0_494
; #define LAS __attribute__((address_space(3)))
; __device__ __forceinline__ void attn_unit(LAS unsigned char* lds, const bf16_t* Qg, const bf16_t* Kg, const bf16_t* Vtg, bf16_t* Og, int bh, int qb, int tid_, int wave, int lane_) {
;     ...
;     const float NINF = -__builtin_inff();
;     int s0 = 0, s1 = 1, s2 = 2;
;     for (int j = 0; j < nt; ++j) {
;         const int relc = 64 * (j - 2 * qb) + 32 * kh - 32 * rg;
;         const int j3 = (j + 3 < nt) ? j + 3 : nt - 1, j2 = (j + 2 < nt) ? j + 2 : nt - 1;
;         const LAS unsigned char* kb = lds + KRING + s1 * KTILE;
;         const LAS unsigned char* vb = lds + s0 * VTILE;
;         if (relc >= 0) {
;             const int thr = (relc == 0) ? r : -1;
; #pragma unroll
;             for (int i = 0; i < 16; ++i) { const int key = (i & 3) + 8 * (i >> 2) + 4 * hi; if (key > thr) sc[i] = NINF; }
;         }
	v_or_b32_e32 v1, s70, v190
	v_bitop3_b32 v2, v190, v0, s70 bitop3:0x36
	v_bitop3_b32 v0, v1, v0, 2 bitop3:0x36
	v_mov_b32_e32 v14, v177
	v_mov_b32_e32 v15, v177
	v_lshlrev_b32_e32 v203, 4, v2
	v_lshlrev_b32_e32 v204, 4, v0
	v_mov_b32_e32 v0, v177
	v_mov_b32_e32 v1, v177
	v_mov_b32_e32 v2, v177
	v_mov_b32_e32 v3, v177
	v_mov_b32_e32 v4, v177
	v_mov_b32_e32 v5, v177
	v_mov_b32_e32 v6, v177
	v_mov_b32_e32 v7, v177
	v_mov_b32_e32 v8, v177
	v_mov_b32_e32 v9, v177
	v_mov_b32_e32 v10, v177
	v_mov_b32_e32 v11, v177
	v_mov_b32_e32 v12, v177
	v_mov_b32_e32 v13, v177
	v_mov_b64_e32 v[30:31], v[14:15]
	v_mov_b64_e32 v[46:47], v[14:15]
	v_mov_b64_e32 v[62:63], v[14:15]
	v_mov_b32_e32 v183, v177
	v_mov_b32_e32 v185, v177
	v_mov_b32_e32 v187, v177
	s_mov_b32 s53, 2
	s_add_i32 s45, s52, 2
	v_lshlrev_b32_e32 v205, 2, v190
	v_lshl_add_u32 v206, v191, 7, 0
	s_sub_i32 s54, s69, s50
	s_mov_b32 s0, 0
	s_mov_b32 s55, 1
	v_mov_b32_e32 v198, 0xf149f2ca
	v_mov_b32_e32 v226, 0
	v_mov_b32_e32 v227, v226
	v_mov_b32_e32 v228, v226
	v_mov_b32_e32 v229, v226
	v_mov_b32_e32 v230, v226
	v_mov_b32_e32 v231, v226
	v_mov_b32_e32 v232, v226
	v_mov_b32_e32 v233, v226
	v_mov_b32_e32 v234, v226
	v_mov_b32_e32 v235, v226
	v_mov_b32_e32 v236, v226
	v_mov_b32_e32 v237, v226
	v_mov_b32_e32 v238, v226
	v_mov_b32_e32 v239, v226
	v_mov_b32_e32 v240, v226
	v_mov_b32_e32 v241, v226
	v_mov_b32_e32 v242, 0xff7fffff
	v_mov_b32_e32 v243, 0
	v_mov_b32_e32 v180, 0
	v_readlane_b32 s56, v255, 55
	v_mov_b64_e32 v[28:29], v[12:13]
	v_mov_b64_e32 v[26:27], v[10:11]
	v_mov_b64_e32 v[24:25], v[8:9]
	v_mov_b64_e32 v[22:23], v[6:7]
	v_mov_b64_e32 v[20:21], v[4:5]
	v_mov_b64_e32 v[18:19], v[2:3]
	v_mov_b64_e32 v[16:17], v[0:1]
	v_mov_b64_e32 v[44:45], v[12:13]
	v_mov_b64_e32 v[42:43], v[10:11]
	v_mov_b64_e32 v[40:41], v[8:9]
	v_mov_b64_e32 v[38:39], v[6:7]
	v_mov_b64_e32 v[36:37], v[4:5]
	v_mov_b64_e32 v[34:35], v[2:3]
	v_mov_b64_e32 v[32:33], v[0:1]
	v_mov_b64_e32 v[60:61], v[12:13]
	v_mov_b64_e32 v[58:59], v[10:11]
	v_mov_b64_e32 v[56:57], v[8:9]
	v_mov_b64_e32 v[54:55], v[6:7]
	v_mov_b64_e32 v[52:53], v[4:5]
	v_mov_b64_e32 v[50:51], v[2:3]
	v_mov_b64_e32 v[48:49], v[0:1]
	s_mov_b32 s57, 0
	s_mov_b64 s[88:89], s[8:9]
	s_add_i32 s1, s54, s56
	s_cmp_lt_i32 s1, 0
	s_mov_b32 s58, s0
	s_cbranch_scc1 .LBB0_489
.LBB0_488:
	s_cmp_eq_u32 s1, 0
	s_cselect_b64 vcc, -1, 0
	v_cndmask_b32_e32 v213, -1, v191, vcc
	v_sub_u32_e32 v213, v213, v205
	v_cmp_gt_i32_e64 s[38:39], 26, v213
	v_cmp_gt_i32_e64 s[40:41], 27, v213
	v_cmp_gt_i32_e64 s[36:37], 25, v213
	s_and_b64 s[38:39], s[40:41], s[38:39]
	v_cmp_gt_i32_e64 s[34:35], 24, v213
	s_and_b64 s[36:37], s[38:39], s[36:37]
	v_cmp_gt_i32_e64 s[30:31], 19, v213
	s_and_b64 s[34:35], s[36:37], s[34:35]
	v_cmp_gt_i32_e64 s[28:29], 18, v213
	s_and_b64 s[30:31], s[34:35], s[30:31]
	v_cmp_gt_i32_e64 s[26:27], 17, v213
	s_and_b64 s[28:29], s[30:31], s[28:29]
	v_cmp_gt_i32_e64 s[24:25], 16, v213
	s_and_b64 s[26:27], s[28:29], s[26:27]
	v_cmp_gt_i32_e64 s[22:23], 11, v213
	s_and_b64 s[24:25], s[26:27], s[24:25]
	v_cmp_gt_i32_e64 s[20:21], 10, v213
	s_and_b64 s[22:23], s[24:25], s[22:23]
	v_cmp_gt_i32_e64 s[18:19], 9, v213
	s_and_b64 s[20:21], s[22:23], s[20:21]
	v_cmp_gt_i32_e64 s[16:17], 8, v213
	s_and_b64 s[18:19], s[20:21], s[18:19]
	v_cmp_gt_i32_e64 s[14:15], 3, v213
	s_and_b64 s[16:17], s[18:19], s[16:17]
	v_cmp_gt_i32_e64 s[12:13], 2, v213
	s_and_b64 s[14:15], s[16:17], s[14:15]
	v_cmp_gt_i32_e64 s[0:1], 1, v213
	s_and_b64 s[12:13], s[14:15], s[12:13]
	v_cmp_gt_i32_e32 vcc, 0, v213
	s_and_b64 s[0:1], s[12:13], s[0:1]
	s_and_b64 vcc, s[0:1], vcc
	v_cndmask_b32_e64 v95, v95, v196, s[40:41]
	v_cndmask_b32_e64 v94, v94, v196, s[38:39]
	v_cndmask_b32_e64 v93, v93, v196, s[36:37]
	v_cndmask_b32_e64 v92, v92, v196, s[34:35]
	v_cndmask_b32_e64 v91, v91, v196, s[30:31]
	v_cndmask_b32_e64 v90, v90, v196, s[28:29]
	v_cndmask_b32_e64 v89, v89, v196, s[26:27]
	v_cndmask_b32_e64 v88, v88, v196, s[24:25]
	v_cndmask_b32_e64 v87, v87, v196, s[22:23]
	v_cndmask_b32_e64 v86, v86, v196, s[20:21]
	v_cndmask_b32_e64 v85, v85, v196, s[18:19]
	v_cndmask_b32_e64 v84, v84, v196, s[16:17]
	v_cndmask_b32_e64 v83, v83, v196, s[14:15]
	v_cndmask_b32_e64 v82, v82, v196, s[12:13]
	v_cndmask_b32_e64 v81, v81, v196, s[0:1]
	v_cndmask_b32_e32 v80, v80, v196, vcc
	s_branch .LBB0_490
; __device__ __forceinline__ float max_xor32(float x) { const u32x2 r = __builtin_amdgcn_permlane32_swap(__float_as_uint(x), __float_as_uint(x), false, false); return fmaxf(__uint_as_float(r.x), __uint_as_float(r.y)); }
; #define MFMA32(a, b, c) __builtin_amdgcn_mfma_f32_32x32x16_bf16((a), (b), (c), 0, 0, 0)
; #define ATT_KRD(dst, g) do { _Pragma("unroll") for (int q_ = 0; q_ < 4; ++q_) dst[q_] = *(const LAS bf16x8*)(kb + kro[q_] + (g) * 128); } while (0)
; __device__ __forceinline__ void attn_unit(LAS unsigned char* lds, const bf16_t* Qg, const bf16_t* Kg, const bf16_t* Vtg, bf16_t* Og, int bh, int qb, int tid_, int wave, int lane_) {
;     ...
;         bf16x8 fa[4], fb[4];
;         ATT_KRD(fa, 0); ATT_KRD(fb, 1);
; #pragma unroll
;         for (int i = 0; i < 16; ++i) sn[i] = 0.f;
;         float mx = sc[0];
; #pragma unroll
;         for (int i = 1; i < 16; ++i) mx = fmaxf(mx, sc[i]);
;         mx = max_xor32(mx);
; #pragma unroll
;         for (int q = 0; q < 4; ++q) sn = MFMA32(fa[q], qf[q], sn);
;         ATT_KRD(fa, 2);
;         __builtin_amdgcn_sched_barrier(0);
;         if (__builtin_amdgcn_ballot_w64(mx > mrun + 8.f) != 0ull) {
;             const float mnew = fmaxf(mrun, mx); const float alpha = __builtin_amdgcn_exp2f(mrun - mnew); mrun = mnew; lrun *= alpha;
; #pragma unroll
;             for (int dt = 0; dt < 4; ++dt) o[dt] = o[dt] * alpha;
;         }
.LBB0_489:
.LBB0_490:
	s_mul_i32 s0, s55, 0x6000
	s_add_i32 s0, s0, 0
	v_add_u32_e32 v148, s0, v199
	ds_read_b128 v[64:67], v148
	v_add_u32_e32 v156, s0, v200
	ds_read_b128 v[144:147], v156
	v_add_u32_e32 v160, s0, v201
	v_add_u32_e32 v192, s0, v202
	ds_read_b128 v[208:211], v192
	ds_read_b128 v[164:167], v148 offset:128
	ds_read_b128 v[152:155], v160
	ds_read_b128 v[168:171], v160 offset:128
	s_waitcnt lgkmcnt(0)
	v_mfma_f32_32x32x16_bf16 v[64:79], v[64:67], v[96:99], v[226:241]
	v_max_f32_e32 v149, v80, v81
	v_max3_f32 v157, v149, v82, v83
	ds_read_b128 v[148:151], v148 offset:256
	s_waitcnt lgkmcnt(5)
	v_mfma_f32_32x32x16_bf16 v[64:79], v[144:147], v[100:103], v[64:79]
	v_max3_f32 v144, v157, v84, v85
	v_max3_f32 v144, v144, v86, v87
	v_max3_f32 v144, v144, v88, v89
	v_max3_f32 v144, v144, v90, v91
	v_max3_f32 v144, v144, v92, v93
	v_max3_f32 v193, v144, v94, v95
	v_mov_b32_e32 v194, v193
	s_waitcnt lgkmcnt(2)
	v_mfma_f32_32x32x16_bf16 v[64:79], v[152:155], v[104:107], v[64:79]
	ds_read_b128 v[172:175], v156 offset:128
	ds_read_b128 v[156:159], v156 offset:256
	ds_read_b128 v[152:155], v160 offset:256
	ds_read_b128 v[160:163], v192 offset:128
	ds_read_b128 v[144:147], v192 offset:256
	v_permlane32_swap_b32_e32 v193, v194
	v_max_f32_e32 v207, v193, v194
	v_mfma_f32_32x32x16_bf16 v[64:79], v[208:211], v[108:111], v[64:79]
	v_cmp_gt_f32_e32 vcc, v207, v242
	s_cbranch_vccz .LBB0_492
	v_add_f32_e32 v192, v207, v243
	v_max_f32_e32 v193, v198, v198
	v_max_f32_e32 v193, v193, v192
	v_sub_f32_e32 v192, v198, v193
	v_sub_f32_e32 v244, v243, v193
	v_exp_f32_e32 v192, v192
	v_mov_b32_e32 v198, v193
	v_mov_b32_e32 v243, v193
	v_mov_b32_e32 v242, 0x41000000
	v_pk_mul_f32 v[62:63], v[62:63], v[192:193] op_sel_hi:[1,0]
	v_pk_mul_f32 v[60:61], v[60:61], v[192:193] op_sel_hi:[1,0]
	v_pk_mul_f32 v[58:59], v[58:59], v[192:193] op_sel_hi:[1,0]
	v_pk_mul_f32 v[56:57], v[56:57], v[192:193] op_sel_hi:[1,0]
	v_pk_mul_f32 v[54:55], v[54:55], v[192:193] op_sel_hi:[1,0]
	v_pk_mul_f32 v[52:53], v[52:53], v[192:193] op_sel_hi:[1,0]
	v_pk_mul_f32 v[50:51], v[50:51], v[192:193] op_sel_hi:[1,0]
	v_pk_mul_f32 v[48:49], v[48:49], v[192:193] op_sel_hi:[1,0]
	v_pk_mul_f32 v[46:47], v[46:47], v[192:193] op_sel_hi:[1,0]
	v_pk_mul_f32 v[44:45], v[44:45], v[192:193] op_sel_hi:[1,0]
	v_pk_mul_f32 v[42:43], v[42:43], v[192:193] op_sel_hi:[1,0]
	v_pk_mul_f32 v[40:41], v[40:41], v[192:193] op_sel_hi:[1,0]
	v_pk_mul_f32 v[38:39], v[38:39], v[192:193] op_sel_hi:[1,0]
	v_pk_mul_f32 v[36:37], v[36:37], v[192:193] op_sel_hi:[1,0]
	v_pk_mul_f32 v[34:35], v[34:35], v[192:193] op_sel_hi:[1,0]
	v_pk_mul_f32 v[32:33], v[32:33], v[192:193] op_sel_hi:[1,0]
	v_pk_mul_f32 v[30:31], v[30:31], v[192:193] op_sel_hi:[1,0]
	v_pk_mul_f32 v[28:29], v[28:29], v[192:193] op_sel_hi:[1,0]
	v_pk_mul_f32 v[26:27], v[26:27], v[192:193] op_sel_hi:[1,0]
	v_pk_mul_f32 v[24:25], v[24:25], v[192:193] op_sel_hi:[1,0]
	v_pk_mul_f32 v[22:23], v[22:23], v[192:193] op_sel_hi:[1,0]
	v_pk_mul_f32 v[20:21], v[20:21], v[192:193] op_sel_hi:[1,0]
	v_pk_mul_f32 v[18:19], v[18:19], v[192:193] op_sel_hi:[1,0]
	v_pk_mul_f32 v[16:17], v[16:17], v[192:193] op_sel_hi:[1,0]
	v_pk_mul_f32 v[14:15], v[14:15], v[192:193] op_sel_hi:[1,0]
	v_pk_mul_f32 v[12:13], v[12:13], v[192:193] op_sel_hi:[1,0]
	v_pk_mul_f32 v[10:11], v[10:11], v[192:193] op_sel_hi:[1,0]
	v_pk_mul_f32 v[8:9], v[8:9], v[192:193] op_sel_hi:[1,0]
	v_pk_mul_f32 v[6:7], v[6:7], v[192:193] op_sel_hi:[1,0]
	v_pk_mul_f32 v[4:5], v[4:5], v[192:193] op_sel_hi:[1,0]
	v_pk_mul_f32 v[2:3], v[2:3], v[192:193] op_sel_hi:[1,0]
	v_pk_mul_f32 v[0:1], v[0:1], v[192:193] op_sel_hi:[1,0]
	v_mul_f32_e32 v180, v180, v192
	v_add_f32_e32 v80, v80, v244
	v_add_f32_e32 v81, v81, v244
	v_add_f32_e32 v82, v82, v244
	v_add_f32_e32 v83, v83, v244
	v_add_f32_e32 v84, v84, v244
	v_add_f32_e32 v85, v85, v244
	v_add_f32_e32 v86, v86, v244
	v_add_f32_e32 v87, v87, v244
	v_add_f32_e32 v88, v88, v244
	v_add_f32_e32 v89, v89, v244
	v_add_f32_e32 v90, v90, v244
	v_add_f32_e32 v91, v91, v244
	v_add_f32_e32 v92, v92, v244
	v_add_f32_e32 v93, v93, v244
	v_add_f32_e32 v94, v94, v244
	v_add_f32_e32 v95, v95, v244
	v_add_f32_e32 v64, v64, v244
	v_add_f32_e32 v65, v65, v244
	v_add_f32_e32 v66, v66, v244
	v_add_f32_e32 v67, v67, v244
	v_add_f32_e32 v68, v68, v244
	v_add_f32_e32 v69, v69, v244
	v_add_f32_e32 v70, v70, v244
	v_add_f32_e32 v71, v71, v244
	v_add_f32_e32 v72, v72, v244
	v_add_f32_e32 v73, v73, v244
	v_add_f32_e32 v74, v74, v244
	v_add_f32_e32 v75, v75, v244
	v_add_f32_e32 v76, v76, v244
	v_add_f32_e32 v77, v77, v244
	v_add_f32_e32 v78, v78, v244
	v_add_f32_e32 v79, v79, v244
	v_sub_f32_e32 v226, 0, v193
	v_mov_b32_e32 v227, v226
	v_mov_b32_e32 v228, v226
	v_mov_b32_e32 v229, v226
	v_mov_b32_e32 v230, v226
	v_mov_b32_e32 v231, v226
	v_mov_b32_e32 v232, v226
	v_mov_b32_e32 v233, v226
	v_mov_b32_e32 v234, v226
	v_mov_b32_e32 v235, v226
	v_mov_b32_e32 v236, v226
	v_mov_b32_e32 v237, v226
	v_mov_b32_e32 v238, v226
	v_mov_b32_e32 v239, v226
	v_mov_b32_e32 v240, v226
	v_mov_b32_e32 v241, v226
; __device__ __forceinline__ unsigned pk2(float a, float b) { f32x2_t v = {a, b}; bf16x2v_t r = __builtin_convertvector(v, bf16x2v_t); return __builtin_bit_cast(unsigned, r); }
; __device__ __forceinline__ void attn_unit(LAS unsigned char* lds, const bf16_t* Qg, const bf16_t* Kg, const bf16_t* Vtg, bf16_t* Og, int bh, int qb, int tid_, int wave, int lane_) {
;     ...
;         float ps = 0.f; u32x4 p0, p1;
; #pragma unroll
;         for (int q = 0; q < 4; ++q) sn = MFMA32(fb[q], qf[4 + q], sn);
; #pragma unroll
;         for (int i = 0; i < 8; ++i) { sc[i] = __builtin_amdgcn_exp2f(sc[i] - mrun); ps += sc[i]; }
;         p0.x = pk2(sc[0], sc[1]); p0.y = pk2(sc[2], sc[3]); p0.z = pk2(sc[4], sc[5]); p0.w = pk2(sc[6], sc[7]);
;         __builtin_amdgcn_sched_barrier(0);
; #pragma unroll
;         for (int dt = 0; dt < 4; ++dt) fb[dt] = *(const LAS bf16x8*)(vb + vro[0] + dt * 4096);
;         __builtin_amdgcn_sched_barrier(0);
;         ATT_ISSUE_K(j3, s0);
;         __builtin_amdgcn_sched_barrier(0);
; #pragma unroll
;         for (int q = 0; q < 4; ++q) sn = MFMA32(fa[q], qf[8 + q], sn);
; #pragma unroll
;         for (int i = 8; i < 12; ++i) { sc[i] = __builtin_amdgcn_exp2f(sc[i] - mrun); ps += sc[i]; }
;         p1.x = pk2(sc[8], sc[9]); p1.y = pk2(sc[10], sc[11]);
;         __builtin_amdgcn_sched_barrier(0);
;         ATT_ISSUE_V(j2, s2);
;         __builtin_amdgcn_sched_barrier(0);
; #pragma unroll
;         for (int dt = 0; dt < 4; ++dt) fa[dt] = *(const LAS bf16x8*)(vb + vro[1] + dt * 4096);
;         { const bf16x8 pf0 = __builtin_bit_cast(bf16x8, p0);
;           o[0] = MFMA32(fb[0], pf0, o[0]); o[1] = MFMA32(fb[1], pf0, o[1]); o[2] = MFMA32(fb[2], pf0, o[2]); o[3] = MFMA32(fb[3], pf0, o[3]); }
; #pragma unroll
;         for (int i = 12; i < 16; ++i) { sc[i] = __builtin_amdgcn_exp2f(sc[i] - mrun); ps += sc[i]; }
;         p1.z = pk2(sc[12], sc[13]); p1.w = pk2(sc[14], sc[15]);
;         lrun += ps;
;         __builtin_amdgcn_sched_barrier(0);
;         { const bf16x8 pf1 = __builtin_bit_cast(bf16x8, p1);
;           o[0] = MFMA32(fa[0], pf1, o[0]); o[1] = MFMA32(fa[1], pf1, o[1]); o[2] = MFMA32(fa[2], pf1, o[2]); o[3] = MFMA32(fa[3], pf1, o[3]); }
;         asm volatile("s_waitcnt vmcnt(5) lgkmcnt(0)" ::: "memory"); __builtin_amdgcn_s_barrier(); asm volatile("" ::: "memory");
;         sc = sn;
;         { const int t = s0; s0 = s1; s1 = s2; s2 = t; }
;     }
.LBB0_492:
	v_mfma_f32_32x32x16_bf16 v[64:79], v[164:167], v[112:115], v[64:79]
	v_exp_f32_e32 v192, v80
	v_exp_f32_e32 v193, v81
	v_exp_f32_e32 v194, v82
	s_waitcnt lgkmcnt(0)
	v_mfma_f32_32x32x16_bf16 v[64:79], v[172:175], v[116:119], v[64:79]
	v_exp_f32_e32 v207, v83
	v_exp_f32_e32 v208, v84
	v_exp_f32_e32 v209, v85
	v_exp_f32_e32 v210, v86
	v_mfma_f32_32x32x16_bf16 v[64:79], v[168:171], v[120:123], v[64:79]
	s_add_i32 s0, s57, 3
	v_exp_f32_e32 v211, v87
	s_cmp_lt_i32 s0, s45
	s_cselect_b32 s0, s0, s44
	s_add_i32 s1, s57, 2
	s_cmp_lt_i32 s57, s52
	s_cselect_b32 s48, s1, s44
	v_cvt_pk_bf16_f32 v246, v192, v193
	v_cvt_pk_bf16_f32 v247, v194, v207
	v_cvt_pk_bf16_f32 v248, v208, v209
	v_cvt_pk_bf16_f32 v249, v210, v211
	v_lshl_add_u32 v218, s58, 14, v206
	v_add_u32_e32 v212, 0x12000, v218
	v_add_u32_e32 v172, v212, v203
	ds_read_b128 v[214:217], v172
	ds_read_b128 v[164:167], v172 offset:4096
	ds_read_b128 v[168:171], v172 offset:8192
	ds_read_b128 v[172:175], v172 offset:12288
	v_add_f32_e32 v192, v193, v192
	v_add_f32_e32 v192, v194, v192
	v_add_f32_e32 v192, v207, v192
	v_add_f32_e32 v192, v208, v192
	v_add_f32_e32 v192, v209, v192
	v_add_f32_e32 v192, v210, v192
	v_add_f32_e32 v194, v211, v192
	s_mul_hi_u32 s1, s0, 0x6000
	s_mulk_i32 s0, 0x6000
	s_add_u32 s0, s92, s0
	s_mul_i32 s12, s58, 0x6000
	s_addc_u32 s1, s93, s1
	s_add_i32 s12, s71, s12
	s_mov_b32 m0, s12
	s_waitcnt lgkmcnt(5)
	v_mfma_f32_32x32x16_bf16 v[64:79], v[160:163], v[124:127], v[64:79]
	global_load_lds_dwordx4 v182, s[0:1]
	s_add_i32 m0, s12, 0x400
	s_nop 0
	global_load_lds_dwordx4 v184, s[0:1]
	s_add_i32 m0, s12, 0x800
	s_nop 0
	global_load_lds_dwordx4 v186, s[0:1]
	v_mfma_f32_32x32x16_bf16 v[64:79], v[148:151], v[128:131], v[64:79]
	v_exp_f32_e32 v220, v88
	v_exp_f32_e32 v221, v89
	v_exp_f32_e32 v222, v90
	v_mfma_f32_32x32x16_bf16 v[64:79], v[156:159], v[132:135], v[64:79]
	v_exp_f32_e32 v223, v91
	v_add_f32_e32 v148, v220, v194
	v_add_f32_e32 v148, v221, v148
	v_add_f32_e32 v148, v222, v148
	v_add_f32_e32 v156, v223, v148
	v_cvt_pk_bf16_f32 v250, v220, v221
	v_cvt_pk_bf16_f32 v251, v222, v223
	v_mfma_f32_32x32x16_bf16 v[64:79], v[152:155], v[136:139], v[64:79]
	v_exp_f32_e32 v220, v92
	v_exp_f32_e32 v221, v93
	v_exp_f32_e32 v222, v94
	v_exp_f32_e32 v223, v95
	s_waitcnt lgkmcnt(0)
	v_mfma_f32_32x32x16_bf16 v[80:95], v[144:147], v[140:143], v[64:79]
	s_lshl_b64 s[0:1], s[48:49], 7
	s_add_u32 s0, s94, s0
	s_addc_u32 s1, s95, s1
	s_lshl_b32 s12, s53, 14
	s_add_i32 s12, s12, 0
	s_add_i32 s12, s12, s68
	s_add_i32 m0, s12, 0x12000
	s_nop 0
	global_load_lds_dwordx4 v176, s[0:1]
	s_add_i32 m0, s12, 0x12400
	s_nop 0
	global_load_lds_dwordx4 v188, s[0:1]
	v_add_u32_e32 v219, v212, v204
	v_mfma_f32_32x32x16_bf16 v[48:63], v[214:217], v[246:249], v[48:63]
	ds_read_b128 v[214:217], v219
	ds_read_b128 v[144:147], v219 offset:4096
	ds_read_b128 v[148:151], v219 offset:8192
	ds_read_b128 v[152:155], v219 offset:12288
	v_mfma_f32_32x32x16_bf16 v[32:47], v[164:167], v[246:249], v[32:47]
	v_add_f32_e32 v213, v220, v156
	v_add_f32_e32 v213, v221, v213
	v_add_f32_e32 v213, v222, v213
	v_add_f32_e32 v213, v223, v213
	v_add_f32_e32 v180, v180, v213
	v_mfma_f32_32x32x16_bf16 v[16:31], v[168:171], v[246:249], v[16:31]
	v_cvt_pk_bf16_f32 v252, v220, v221
	v_cvt_pk_bf16_f32 v253, v222, v223
	v_mfma_f32_32x32x16_bf16 v[0:15], v[172:175], v[246:249], v[0:15]
	s_waitcnt lgkmcnt(0)
	v_mfma_f32_32x32x16_bf16 v[48:63], v[214:217], v[250:253], v[48:63]
	s_waitcnt vmcnt(5) lgkmcnt(0)
	s_barrier
	s_add_i32 s57, s57, 1
	s_add_i32 s56, s56, 64
	s_cmp_eq_u32 s45, s57
	v_mfma_f32_32x32x16_bf16 v[32:47], v[144:147], v[250:253], v[32:47]
	v_mfma_f32_32x32x16_bf16 v[16:31], v[148:151], v[250:253], v[16:31]
	v_mfma_f32_32x32x16_bf16 v[0:15], v[152:155], v[250:253], v[0:15]
	s_cbranch_scc1 .LBB0_495
	s_mov_b32 s0, s55
	s_mov_b32 s55, s53
	s_mov_b32 s53, s58
	s_add_i32 s1, s54, s56
	s_cmp_lt_i32 s1, 0
	s_mov_b32 s58, s0
	s_cbranch_scc0 .LBB0_488
	s_branch .LBB0_489
